# k23 + diff in-proj tile order swapped (tile index xor 512): the V-region tiles with the dword-store-heavy epilogue run in the first round instead of at the phase tail
# speedup vs baseline: 1.0032x; 1.0032x over previous
.LBB0_1064:
	s_xor_b32 s22, s52, 0x200
	s_ashr_i32 s22, s22, 3
	s_lshl_b32 s31, s22, 1
	s_and_b32 s30, s22, -16
	s_and_b32 s31, s31, 14
	s_or_b32 s30, s31, s30
	s_bfe_u32 s31, s22, 0x10003
	s_or_b32 s23, s22, 63
	s_or_b32 s30, s30, s31
	s_cmpk_lt_i32 s23, 0x80
	s_cselect_b32 s22, s30, s22
	s_lshl_b32 s23, s52, 7
	s_and_b32 s23, s23, 0x380
	s_add_i32 s22, s22, s23
	s_ashr_i32 s23, s22, 31
	s_lshr_b32 s30, s23, 27
	s_add_i32 s30, s22, s30
	s_ashr_i32 s31, s30, 5
	s_andn2_b32 s30, s30, 31
	s_sub_i32 s30, s22, s30
	s_lshr_b32 s23, s23, 25
	s_add_i32 s22, s22, s23
	s_ashr_i32 s23, s30, 31
	s_lshr_b32 s23, s23, 29
	s_ashr_i32 s22, s22, 7
	s_add_i32 s23, s30, s23
	s_ashr_i32 s23, s23, 3
	s_lshl_b32 s38, s22, 2
	s_add_i32 s38, s38, s23
	s_sub_i32 s31, s31, s38
	s_lshl_b32 s42, s31, 3
	s_add_i32 s42, s42, s30
	s_lshl_b32 s22, s22, 10
	s_lshl_b32 s38, s23, 8
	s_add_i32 s38, s38, s22
	s_lshl_b32 s53, s42, 7
	s_ashr_i32 s44, s42, 3
	s_cmp_lg_u32 s44, 2
	s_cselect_b64 s[22:23], -1, 0
	s_mov_b64 s[30:31], -1
	s_and_b64 vcc, exec, s[22:23]
	s_mov_b32 s39, 0x30000
	s_cbranch_vccz .LBB0_1068
	v_mov_b32_e32 v8, v188
	s_mov_b32 s30, 0x20000
	v_ashrrev_i32_e32 v9, 3, v8
	v_lshlrev_b32_e32 v4, 4, v8
	v_and_b32_e32 v176, 0x70, v4
	v_add_u32_e32 v4, s53, v9
	v_add_u32_e32 v0, s38, v9
	v_ashrrev_i32_e32 v5, 31, v4
	v_ashrrev_i32_e32 v1, 31, v0
	v_lshlrev_b64 v[4:5], 11, v[4:5]
	v_xor_b32_e32 v10, v9, v8
	v_lshlrev_b64 v[0:1], 11, v[0:1]
	v_lshl_add_u64 v[6:7], s[2:3], 0, v[4:5]
	v_lshlrev_b32_e32 v10, 4, v10
	v_lshl_add_u64 v[2:3], s[0:1], 0, v[0:1]
	v_lshl_add_u64 v[6:7], v[6:7], 0, v[176:177]
	v_and_b32_e32 v10, 0x70, v10
	v_lshl_add_u64 v[2:3], v[2:3], 0, v[176:177]
	v_lshl_or_b32 v176, v9, 7, v10
	v_lshlrev_b32_e32 v12, 7, v8
	v_lshrrev_b32_e32 v9, 4, v8
	v_bfe_u32 v14, v8, 4, 2
	v_and_b32_e32 v15, 7, v8
	v_add_co_u32_e32 v8, vcc, s39, v6
	v_bitop3_b32 v16, v9, v15, 3 bitop3:0x6c
	s_nop 0
	v_addc_co_u32_e32 v9, vcc, 0, v7, vcc
	v_add_co_u32_e32 v10, vcc, s30, v6
	s_mov_b32 s31, 0x10000
	s_nop 0
	v_addc_co_u32_e32 v11, vcc, 0, v7, vcc
	global_load_dwordx4 v[20:23], v[8:9], off
	global_load_dwordx4 v[24:27], v[10:11], off
	v_add_co_u32_e32 v8, vcc, s31, v6
	s_mov_b32 s40, 0x70000
	s_nop 0
	v_addc_co_u32_e32 v9, vcc, 0, v7, vcc
	v_add_co_u32_e32 v10, vcc, s40, v2
	s_mov_b32 s40, 0x60000
	s_nop 0
	v_addc_co_u32_e32 v11, vcc, 0, v3, vcc
	global_load_dwordx4 v[40:43], v[8:9], off
	global_load_dwordx4 v[48:51], v[10:11], off
	v_add_co_u32_e32 v8, vcc, s40, v2
	s_mov_b32 s40, 0x50000
	s_nop 0
	v_addc_co_u32_e32 v9, vcc, 0, v3, vcc
	v_add_co_u32_e32 v10, vcc, s40, v2
	s_mov_b32 s40, 0x40000
	s_nop 0
	v_addc_co_u32_e32 v11, vcc, 0, v3, vcc
	global_load_dwordx4 v[60:63], v[8:9], off
	global_load_dwordx4 v[68:71], v[10:11], off
	v_add_co_u32_e32 v8, vcc, s40, v2
	v_and_b32_e32 v13, 0xffffc780, v12
	s_nop 0
	v_addc_co_u32_e32 v9, vcc, 0, v3, vcc
	v_add_co_u32_e32 v10, vcc, s39, v2
	v_and_b32_e32 v12, 0x2780, v12
	s_nop 0
	v_addc_co_u32_e32 v11, vcc, 0, v3, vcc
	global_load_dwordx4 v[80:83], v[8:9], off
	global_load_dwordx4 v[88:91], v[10:11], off
	v_add_co_u32_e32 v8, vcc, s30, v2
	v_bitop3_b32 v14, v14, v15, 4 bitop3:0x36
	s_nop 0
	v_addc_co_u32_e32 v9, vcc, 0, v3, vcc
	v_add_co_u32_e32 v10, vcc, s31, v2
	v_mov_b32_e32 v140, 0
	s_nop 0
	v_addc_co_u32_e32 v11, vcc, 0, v3, vcc
	global_load_dwordx4 v[104:107], v[8:9], off
	global_load_dwordx4 v[112:115], v[10:11], off
	global_load_dwordx4 v[100:103], v[6:7], off
	global_load_dwordx4 v[116:119], v[2:3], off
	v_lshlrev_b32_e32 v2, 4, v16
	v_or_b32_e32 v185, v13, v2
	v_or_b32_e32 v184, v12, v2
	v_lshlrev_b32_e32 v2, 4, v14
	v_or_b32_e32 v183, v13, v2
	v_or_b32_e32 v182, v12, v2
	v_lshlrev_b32_e32 v2, 4, v15
	v_or_b32_e32 v0, v0, v2
	v_or_b32_e32 v4, v4, v2
	v_lshl_add_u64 v[178:179], s[34:35], 0, v[0:1]
	v_lshl_add_u64 v[180:181], s[50:51], 0, v[4:5]
	s_mov_b64 s[30:31], 0
	v_mov_b32_e32 v141, v140
	v_mov_b32_e32 v142, v140
	v_mov_b32_e32 v143, v140
	v_mov_b32_e32 v0, v140
	v_mov_b32_e32 v1, v140
	v_mov_b32_e32 v2, v140
	v_mov_b32_e32 v3, v140
	v_mov_b32_e32 v4, v140
	v_mov_b32_e32 v5, v140
	v_mov_b32_e32 v6, v140
	v_mov_b32_e32 v7, v140
	v_mov_b32_e32 v8, v140
	v_mov_b32_e32 v9, v140
	v_mov_b32_e32 v10, v140
	v_mov_b32_e32 v11, v140
	v_mov_b32_e32 v12, v140
	v_mov_b32_e32 v13, v140
	v_mov_b32_e32 v14, v140
	v_mov_b32_e32 v15, v140
	v_mov_b32_e32 v16, v140
	v_mov_b32_e32 v17, v140
	v_mov_b32_e32 v18, v140
	v_mov_b32_e32 v19, v140
	v_mov_b32_e32 v28, v140
	v_mov_b32_e32 v29, v140
	v_mov_b32_e32 v30, v140
	v_mov_b32_e32 v31, v140
	v_mov_b32_e32 v32, v140
	v_mov_b32_e32 v33, v140
	v_mov_b32_e32 v34, v140
	v_mov_b32_e32 v35, v140
	v_mov_b32_e32 v36, v140
	v_mov_b32_e32 v37, v140
	v_mov_b32_e32 v38, v140
	v_mov_b32_e32 v39, v140
	v_mov_b32_e32 v44, v140
	v_mov_b32_e32 v45, v140
	v_mov_b32_e32 v46, v140
	v_mov_b32_e32 v47, v140
	v_mov_b32_e32 v52, v140
	v_mov_b32_e32 v53, v140
	v_mov_b32_e32 v54, v140
	v_mov_b32_e32 v55, v140
	v_mov_b32_e32 v56, v140
	v_mov_b32_e32 v57, v140
	v_mov_b32_e32 v58, v140
	v_mov_b32_e32 v59, v140
	v_mov_b32_e32 v64, v140
	v_mov_b32_e32 v65, v140
	v_mov_b32_e32 v66, v140
	v_mov_b32_e32 v67, v140
	v_mov_b32_e32 v72, v140
	v_mov_b32_e32 v73, v140
	v_mov_b32_e32 v74, v140
	v_mov_b32_e32 v75, v140
	v_mov_b32_e32 v76, v140
	v_mov_b32_e32 v77, v140
	v_mov_b32_e32 v78, v140
	v_mov_b32_e32 v79, v140
	v_mov_b32_e32 v84, v140
	v_mov_b32_e32 v85, v140
	v_mov_b32_e32 v86, v140
	v_mov_b32_e32 v87, v140
	v_mov_b32_e32 v92, v140
	v_mov_b32_e32 v93, v140
	v_mov_b32_e32 v94, v140
	v_mov_b32_e32 v95, v140
	v_mov_b32_e32 v96, v140
	v_mov_b32_e32 v97, v140
	v_mov_b32_e32 v98, v140
	v_mov_b32_e32 v99, v140
	v_mov_b32_e32 v108, v140
	v_mov_b32_e32 v109, v140
	v_mov_b32_e32 v110, v140
	v_mov_b32_e32 v111, v140
	v_mov_b32_e32 v120, v140
	v_mov_b32_e32 v121, v140
	v_mov_b32_e32 v122, v140
	v_mov_b32_e32 v123, v140
	v_mov_b32_e32 v124, v140
	v_mov_b32_e32 v125, v140
	v_mov_b32_e32 v126, v140
	v_mov_b32_e32 v127, v140
	v_mov_b32_e32 v128, v140
	v_mov_b32_e32 v129, v140
	v_mov_b32_e32 v130, v140
	v_mov_b32_e32 v131, v140
	v_mov_b32_e32 v132, v140
	v_mov_b32_e32 v133, v140
	v_mov_b32_e32 v134, v140
	v_mov_b32_e32 v135, v140
	v_mov_b32_e32 v136, v140
	v_mov_b32_e32 v137, v140
	v_mov_b32_e32 v138, v140
	v_mov_b32_e32 v139, v140
	v_mov_b32_e32 v144, v140
	v_mov_b32_e32 v145, v140
	v_mov_b32_e32 v146, v140
	v_mov_b32_e32 v147, v140
	v_mov_b32_e32 v148, v140
	v_mov_b32_e32 v149, v140
	v_mov_b32_e32 v150, v140
	v_mov_b32_e32 v151, v140
	v_mov_b32_e32 v152, v140
	v_mov_b32_e32 v153, v140
	v_mov_b32_e32 v154, v140
	v_mov_b32_e32 v155, v140
	v_mov_b32_e32 v156, v140
	v_mov_b32_e32 v157, v140
	v_mov_b32_e32 v158, v140
	v_mov_b32_e32 v159, v140
	v_mov_b32_e32 v160, v140
	v_mov_b32_e32 v161, v140
	v_mov_b32_e32 v162, v140
	v_mov_b32_e32 v163, v140
	v_mov_b32_e32 v164, v140
	v_mov_b32_e32 v165, v140
	v_mov_b32_e32 v166, v140
	v_mov_b32_e32 v167, v140
	v_mov_b32_e32 v168, v140
	v_mov_b32_e32 v169, v140
	v_mov_b32_e32 v170, v140
	v_mov_b32_e32 v171, v140
	v_mov_b32_e32 v172, v140
	v_mov_b32_e32 v173, v140
	v_mov_b32_e32 v174, v140
	v_mov_b32_e32 v175, v140
	s_mov_b32 s40, 0x820000
	s_mov_b32 s41, 0x830000
	s_setprio 2
	v_readlane_b32 s98, v253, 3
	v_readlane_b32 s99, v253, 4
	v_and_b32_e32 v236, 15, v188
	v_bfe_u32 v237, v188, 4, 2
	v_lshrrev_b32_e32 v238, 2, v236
	v_sub_u32_e32 v238, 0, v238
	v_and_b32_e32 v238, 3, v238
	v_xor_b32_e32 v237, v237, v238
	v_lshlrev_b32_e32 v237, 4, v237
	v_lshl_or_b32 v237, v236, 6, v237
	v_bfe_u32 v238, v188, 7, 1
	v_lshl_or_b32 v185, v238, 13, v237
	v_bfe_u32 v238, v188, 6, 1
	v_lshl_or_b32 v184, v238, 12, v237
	v_add_u32_e32 v184, 0x4000, v184
	v_lshrrev_b32_e32 v236, 3, v188
	v_bfe_u32 v237, v188, 2, 1
	v_lshrrev_b32_e32 v238, 2, v236
	v_sub_u32_e32 v238, 0, v238
	v_and_b32_e32 v238, 3, v238
	v_and_b32_e32 v239, 3, v188
	v_xor_b32_e32 v238, v239, v238
	v_lshlrev_b32_e32 v238, 4, v238
	v_xor_b32_e32 v236, v236, v237
	v_lshl_or_b32 v238, v236, 6, v238
	v_mul_u32_u24_e32 v237, 0x6000, v237
	v_add_u32_e32 v183, v237, v238
	s_mov_b32 m0, 0
	s_sub_u32 vcc_lo, s30, s98
	v_add_u32_e32 v186, vcc_lo, v178
	v_add_u32_e32 v187, vcc_lo, v180
	s_barrier
	s_waitcnt vmcnt(0)
	ds_write_b128 v183, v[116:119]
	ds_write_b128 v183, v[112:115] offset:2048
	ds_write_b128 v183, v[104:107] offset:4096
	ds_write_b128 v183, v[88:91] offset:6144
	ds_write_b128 v183, v[80:83] offset:8192
	ds_write_b128 v183, v[68:71] offset:10240
	ds_write_b128 v183, v[60:63] offset:12288
	ds_write_b128 v183, v[48:51] offset:14336
	ds_write_b128 v183, v[100:103] offset:16384
	ds_write_b128 v183, v[40:43] offset:18432
	ds_write_b128 v183, v[24:27] offset:20480
	ds_write_b128 v183, v[20:23] offset:22528
	v_cmp_gt_u32_e32 vcc, 0x6000, v183
	v_add_u32_e32 v182, 0xc000, v183
	v_add_u32_e32 v183, 0xffffa000, v183
	s_nop 0
	v_cndmask_b32_e32 v183, v183, v182, vcc
	v_add_u32_e32 v116, s26, v186
	global_load_dwordx4 v[116:119], v116, s[98:99] offset:128
	v_add_u32_e32 v112, s27, v186
	global_load_dwordx4 v[112:115], v112, s[98:99] offset:128
	v_add_u32_e32 v104, s20, v186
	global_load_dwordx4 v[104:107], v104, s[98:99] offset:128
	v_add_u32_e32 v88, s21, v186
	global_load_dwordx4 v[88:91], v88, s[98:99] offset:128
	v_add_u32_e32 v80, s56, v186
	global_load_dwordx4 v[80:83], v80, s[98:99] offset:128
	v_add_u32_e32 v68, s57, v186
	global_load_dwordx4 v[68:71], v68, s[98:99] offset:128
	v_add_u32_e32 v60, s24, v186
	global_load_dwordx4 v[60:63], v60, s[98:99] offset:128
	v_add_u32_e32 v48, s96, v186
	global_load_dwordx4 v[48:51], v48, s[98:99] offset:128
	v_add_u32_e32 v100, s25, v187
	global_load_dwordx4 v[100:103], v100, s[98:99] offset:128
	v_add_u32_e32 v40, s33, v187
	global_load_dwordx4 v[40:43], v40, s[98:99] offset:128
	v_add_u32_e32 v24, s40, v187
	global_load_dwordx4 v[24:27], v24, s[98:99] offset:128
	v_add_u32_e32 v20, s41, v187
	global_load_dwordx4 v[20:23], v20, s[98:99] offset:128
	s_add_u32 s30, s30, 0x80
	s_addc_u32 s31, s31, 0
